# P4 tile order variant: tile type = round for every workgroup (Q, K, V, ZS in rounds 0..3), lock-step within each XCD
# baseline (speedup 1.0000x reference)
; __device__ __forceinline__ int tid_of(int wave) { return wave * 64 + lane_id(); }
; #define PG8_STAGE(bufoff, gbase, voff) do { _Pragma("unroll") for (int _i = 0; _i < 2; ++_i) \
;         __builtin_amdgcn_global_load_lds((const unsigned*)((const char*)(gbase) + (voff)[_i]), (PG8_LAS unsigned*)(lds + (bufoff) + ldsw + _i * 8192), 16, 0, 0); } while (0)
; #define PG8_WAIT_V(n) asm volatile("s_waitcnt vmcnt(" #n ")" ::: "memory")
; #define PG8_BAR __builtin_amdgcn_s_barrier()
; #define tid tid_of(wave)
; #define lane lane_id()
; template <class Epi, class Sched, bool ALIGN_EPI = false, bool SP2 = false>
; __device__ __forceinline__ void gemm_phase(PG8_LAS unsigned char* lds, const Gemm g, const Sched& S, const Epi& E, const int wave_) {
;     const int tid = tid_of(wave_), wid = wave_, lane = tid & 63, wr = wid >> 2, wc = wid & 3, fr = lane & 15, fq = lane >> 4;
;     const int K = g.K, nt = K / BK;
;     unsigned voffA[2], voffB[2];
; #pragma unroll
;     for (int i = 0; i < 2; ++i) { int R, C; stage_rc(tid * 16 + i * 8192, R, C); const int Rb = Epi::PERM ? ((R & ~31) + perm32(R & 31)) : R;
;         voffA[i] = (unsigned)(R * K + C) * 2u; voffB[i] = (unsigned)(Rb * K + C) * 2u; }
;     const size_t kstep = (size_t)(BK * 2);
;     const size_t hstep = (size_t)HALF * K * 2;
;     const size_t tstep = 2 * hstep;
;     const unsigned ldsw = (unsigned)wid * 1024u;
;     const int aoff = lds_byte(wr * 64 + fr, fq * 8), boff = lds_byte(wc * 32 + fr, fq * 8);
;     ...
;     const char* cA = (const char*)g.A + (size_t)cur.pm * tstep; const char* cB = (const char*)g.Bt + (size_t)cur.pn * tstep;
;     S.a_ready(cur);
;     if constexpr (SP2) {
;         PG8_STAGE(PG8_SB(0, 0), cB, voffB); PG8_STAGE(PG8_SB(0, 1), cB + hstep, voffB); PG8_STAGE(PG8_SA(0, 0), cA, voffA); PG8_STAGE(PG8_SA(0, 1), cA + hstep, voffA);
;         if (wr == 1) PG8_BAR;
;         PG8_WAIT_V(2); PG8_BAR;
;         PG8_STAGE(PG8_SB(1, 0), cB + kstep, voffB); PG8_STAGE(PG8_SA(1, 0), cA + kstep, voffA); PG8_STAGE(PG8_SB(1, 1), cB + hstep + kstep, voffB);
;         PG8_WAIT_V(6); PG8_BAR;
;     } else {
;         PG8_STAGE(PG8_SB(0, 0), cB, voffB); PG8_STAGE(PG8_SA(0, 0), cA, voffA); PG8_STAGE(PG8_SB(0, 1), cB + hstep, voffB); PG8_STAGE(PG8_SA(0, 1), cA + hstep, voffA);
;         if (wr == 1) PG8_BAR;
;         PG8_WAIT_V(4); PG8_BAR;
.LBB0_482:
	s_andn2_b64 vcc, exec, s[0:1]
	s_cbranch_vccnz .LBB0_534
	s_lshr_b32 s98, s6, 2
	s_and_b32 s98, s98, 3
	s_lshl_b32 s98, s98, 3
	s_lshr_b32 s99, s6, 4
	s_lshl_b32 s99, s99, 2
	s_add_i32 s98, s98, s99
	s_and_b32 s99, s6, 3
	s_add_i32 s6, s98, s99
	v_readlane_b32 s1, v248, 22
	s_lshl_b32 s44, s1, 10
	v_lshl_add_u32 v0, v195, 4, s44
	s_waitcnt lgkmcnt(0)
	v_ashrrev_i32_e32 v1, 31, v0
	v_lshrrev_b32_e32 v1, 22, v1
	v_add_u32_e32 v1, v0, v1
	v_ashrrev_i32_e32 v8, 10, v1
	v_mul_i32_i24_e32 v1, 0x400, v8
	v_sub_u32_e32 v1, v0, v1
	v_lshrrev_b32_e32 v2, 4, v1
	v_bitop3_b32 v1, v2, v1, 32 bitop3:0x6c
	v_ashrrev_i32_e32 v3, 31, v1
	v_lshrrev_b32_e32 v3, 26, v3
	v_add_u32_e32 v3, v1, v3
	v_lshlrev_b32_e32 v2, 3, v8
	v_ashrrev_i32_e32 v9, 6, v3
	v_and_b32_e32 v3, 0xc0, v3
	v_and_b32_e32 v2, -16, v2
	v_sub_u32_e32 v1, v1, v3
	v_mov_b32_e32 v3, 1
	v_add_u32_e32 v2, v9, v2
	v_ashrrev_i16_sdwa v1, v3, sext(v1) dst_sel:DWORD dst_unused:UNUSED_PAD src0_sel:DWORD src1_sel:BYTE_0
	v_lshlrev_b32_e32 v4, 5, v8
	v_bfe_i32 v10, v1, 0, 16
	v_lshlrev_b32_e32 v1, 1, v2
	v_lshrrev_b32_e32 v5, 2, v2
	v_and_b32_e32 v6, 3, v9
	s_mov_b32 s1, 0xfffe0
	v_and_b32_e32 v4, 32, v4
	v_and_b32_e32 v1, 24, v1
	v_and_b32_e32 v5, 4, v5
	v_and_or_b32 v6, v2, s1, v6
	v_or3_b32 v1, v6, v5, v1
	v_add_lshl_u32 v4, v4, v10, 1
	v_add_u32_e32 v0, 0x2000, v0
	v_lshl_add_u32 v130, v1, 12, v4
	v_ashrrev_i32_e32 v1, 31, v0
	v_lshrrev_b32_e32 v1, 22, v1
	v_add_u32_e32 v1, v0, v1
	v_ashrrev_i32_e32 v11, 10, v1
	v_mul_i32_i24_e32 v1, 0x400, v11
	v_sub_u32_e32 v0, v0, v1
	v_lshrrev_b32_e32 v1, 4, v0
	v_bitop3_b32 v0, v1, v0, 32 bitop3:0x6c
	v_lshl_add_u32 v128, v2, 12, v4
	v_ashrrev_i32_e32 v2, 31, v0
	v_lshrrev_b32_e32 v2, 26, v2
	v_add_u32_e32 v2, v0, v2
	v_ashrrev_i32_e32 v12, 6, v2
	v_and_b32_e32 v2, 0xffc0, v2
	s_lshr_b32 s0, s67, 8
	v_sub_u32_e32 v0, v0, v2
	v_lshrrev_b16_e32 v2, 7, v0
	s_cmp_eq_u32 s0, 1
	v_lshlrev_b32_e32 v1, 3, v11
	v_and_b32_e32 v2, 1, v2
	s_cselect_b64 s[12:13], -1, 0
	s_ashr_i32 s5, s4, 31
	s_ashr_i32 s7, s6, 31
	v_and_b32_e32 v1, -16, v1
	v_add_u16_e32 v0, v0, v2
	s_lshl_b64 s[14:15], s[4:5], 20
	s_lshl_b64 s[16:17], s[6:7], 20
	v_readlane_b32 s18, v248, 31
	v_add_u32_e32 v1, v12, v1
	v_ashrrev_i16_sdwa v0, v3, sext(v0) dst_sel:DWORD dst_unused:UNUSED_PAD src0_sel:DWORD src1_sel:BYTE_0
	v_readlane_b32 s19, v248, 32
	s_add_u32 s40, s18, s16
	v_lshlrev_b32_e32 v4, 5, v11
	v_bfe_i32 v13, v0, 0, 16
	v_lshlrev_b32_e32 v0, 1, v1
	v_lshrrev_b32_e32 v2, 2, v1
	v_and_b32_e32 v3, 3, v12
	s_addc_u32 s41, s19, s17
	s_add_i32 s45, s44, 0
	v_and_b32_e32 v4, 32, v4
	v_and_b32_e32 v0, 24, v0
	v_and_b32_e32 v2, 4, v2
	v_and_or_b32 v3, v1, s1, v3
	s_add_i32 m0, s45, 0x10000
	s_add_i32 s1, s45, 0x12000
	v_or3_b32 v0, v3, v2, v0
	v_add_lshl_u32 v2, v4, v13, 1
	s_add_u32 s16, s40, 0x80000
	v_lshl_add_u32 v134, v0, 12, v2
	s_addc_u32 s17, s41, 0
	s_add_i32 s5, s45, 0x14000
	s_add_i32 s7, s45, 0x16000
	global_load_lds_dwordx4 v130, s[40:41]
	s_mov_b32 m0, s1
	s_add_u32 s36, s38, s14
	global_load_lds_dwordx4 v134, s[40:41]
	s_mov_b32 m0, s5
	s_addc_u32 s37, s39, s15
	s_add_i32 s46, s45, 0x2000
	global_load_lds_dwordx4 v130, s[16:17]
	s_mov_b32 m0, s7
	s_add_u32 s14, s36, 0x80000
	global_load_lds_dwordx4 v134, s[16:17]
	s_mov_b32 m0, s45
	v_lshl_add_u32 v132, v1, 12, v2
	s_addc_u32 s15, s37, 0
	s_add_i32 s47, s45, 0x4000
	global_load_lds_dwordx4 v128, s[36:37]
	s_mov_b32 m0, s46
	s_add_i32 s48, s45, 0x6000
	global_load_lds_dwordx4 v132, s[36:37]
	s_mov_b32 m0, s47
	v_mov_b32_e32 v137, 0
	global_load_lds_dwordx4 v128, s[14:15]
	s_mov_b32 m0, s48
	v_mov_b32_e32 v131, v137
	global_load_lds_dwordx4 v132, s[14:15]
	v_mov_b32_e32 v135, v137
	v_mov_b32_e32 v129, v137
	v_mov_b32_e32 v133, v137
	s_mov_b32 s49, 0
	s_mov_b64 s[14:15], 0x80000
	s_cmp_lg_u32 s0, 1
	v_lshl_add_u64 v[6:7], s[40:41], 0, v[130:131]
	v_lshl_add_u64 v[4:5], s[40:41], 0, v[134:135]
	v_lshl_add_u64 v[2:3], s[36:37], 0, v[128:129]
	v_lshl_add_u64 v[0:1], s[36:37], 0, v[132:133]
	s_cbranch_scc1 .LBB0_485
	s_barrier

;     __host__ __device__ bool next(int i, Unit& u) const {
;         const long L = (long)i * G + c; if (L >= nwg) return false;
;         int wgid = (int)L; { const int q = nwg / NXCD, r = nwg % NXCD, xcd = wgid % NXCD, off = wgid / NXCD; wgid = (xcd < r ? xcd * (q + 1) : r * (q + 1) + (xcd - r) * q) + off; }
;         const int nig = WGM * nN, gid = wgid / nig, fm = gid * WGM, gsz = (nM - fm) < WGM ? (nM - fm) : WGM;
;         u.pm = fm + ((wgid % nig) % gsz); u.pn = (wgid % nig) / gsz; return true;
.LBB0_493:
	s_ashr_i32 s5, s5, 3
	s_add_i32 s5, s28, s5
	s_ashr_i32 s7, s5, 31
	s_lshr_b32 s7, s7, 24
	s_add_i32 s7, s5, s7
	s_ashr_i32 s26, s7, 8
	s_lshl_b32 s27, s26, 3
	s_sub_i32 s26, 32, s27
	s_min_i32 s28, s26, 8
	s_abs_i32 s26, s28
	v_cvt_f32_u32_e32 v0, s26
	s_sub_i32 s30, 0, s26
	s_and_b32 s7, s7, 0xffffff00
	s_sub_i32 s5, s5, s7
	v_rcp_iflag_f32_e32 v0, v0
	s_abs_i32 s7, s5
	s_xor_b32 s29, s5, s28
	s_ashr_i32 s29, s29, 31
	v_mul_f32_e32 v0, 0x4f7ffffe, v0
	v_cvt_u32_f32_e32 v0, v0
	s_nop 0
	v_readfirstlane_b32 s31, v0
	s_mul_i32 s30, s30, s31
	s_mul_hi_u32 s30, s31, s30
	s_add_i32 s31, s31, s30
	s_mul_hi_u32 s30, s7, s31
	s_mul_i32 s31, s30, s26
	s_sub_i32 s7, s7, s31
	s_add_i32 s34, s30, 1
	s_sub_i32 s31, s7, s26
	s_cmp_ge_u32 s7, s26
	s_cselect_b32 s30, s34, s30
	s_cselect_b32 s7, s31, s7
	s_add_i32 s31, s30, 1
	s_cmp_ge_u32 s7, s26
	s_cselect_b32 s7, s31, s30
	s_xor_b32 s7, s7, s29
	s_sub_i32 s26, s7, s29
	s_mul_i32 s7, s26, s28
	s_sub_i32 s5, s5, s7
	s_add_i32 s28, s27, s5
	s_lshr_b32 s98, s26, 2
	s_and_b32 s98, s98, 3
	s_lshl_b32 s98, s98, 3
	s_lshr_b32 s99, s26, 4
	s_lshl_b32 s99, s99, 2
	s_add_i32 s98, s98, s99
	s_and_b32 s99, s26, 3
	s_add_i32 s26, s98, s99
